# v88 + counted waits: backward-pass output stage waits vmcnt(3) per row instead of vmcnt(0) before the first row
# speedup vs baseline: 1.0077x; 1.0077x over previous
.Lrg_d1:
	v_sub_u32_e32 v10, 0x7f, v197
	v_lshl_or_b32 v6, v10, 12, v7
	v_lshlrev_b32_e32 v9, 5, v10
	s_waitcnt lgkmcnt(3)
	v_lshlrev_b32_e32 v80, 16, v2
	v_and_b32_e32 v81, 0xffff0000, v2
	v_lshlrev_b32_e32 v82, 16, v3
	v_and_b32_e32 v83, 0xffff0000, v3
	v_lshlrev_b32_e32 v84, 16, v4
	v_and_b32_e32 v85, 0xffff0000, v4
	v_lshlrev_b32_e32 v86, 16, v5
	v_and_b32_e32 v87, 0xffff0000, v5
	s_waitcnt vmcnt(3)
	v_lshlrev_b32_e32 v88, 16, v124
	v_and_b32_e32 v89, 0xffff0000, v124
	v_lshlrev_b32_e32 v90, 16, v125
	v_and_b32_e32 v91, 0xffff0000, v125
	v_lshlrev_b32_e32 v92, 16, v126
	v_and_b32_e32 v93, 0xffff0000, v126
	v_lshlrev_b32_e32 v94, 16, v127
	v_and_b32_e32 v95, 0xffff0000, v127
	v_add_f32_e32 v80, v88, v80
	v_add_f32_e32 v81, v89, v81
	v_add_f32_e32 v82, v90, v82
	v_add_f32_e32 v83, v91, v83
	v_add_f32_e32 v84, v92, v84
	v_add_f32_e32 v85, v93, v85
	v_add_f32_e32 v86, v94, v86
	v_add_f32_e32 v87, v95, v87
	v_add_f32_e32 v88, v80, v81
	v_add_f32_e32 v89, v82, v83
	v_add_f32_e32 v90, v84, v85
	v_add_f32_e32 v91, v86, v87
	v_mul_f32_e32 v12, v80, v80
	v_mul_f32_e32 v13, v82, v82
	v_mul_f32_e32 v14, v84, v84
	v_mul_f32_e32 v15, v86, v86
	v_add_f32_e32 v88, v88, v89
	v_add_f32_e32 v90, v90, v91
	v_fmac_f32_e32 v12, v81, v81
	v_fmac_f32_e32 v13, v83, v83
	v_fmac_f32_e32 v14, v85, v85
	v_fmac_f32_e32 v15, v87, v87
	v_add_f32_e32 v92, v88, v90
	v_add_f32_e32 v12, v12, v13
	v_add_f32_e32 v14, v14, v15
	v_add_f32_e32 v93, v12, v14
	v_add_f32_dpp v92, v92, v92 quad_perm:[1,0,3,2] row_mask:0xf bank_mask:0xf
	v_cvt_pk_bf16_f32 v80, v80, v81
	v_add_f32_dpp v93, v93, v93 quad_perm:[1,0,3,2] row_mask:0xf bank_mask:0xf
	v_add_f32_dpp v92, v92, v92 quad_perm:[2,3,0,1] row_mask:0xf bank_mask:0xf
	v_cvt_pk_bf16_f32 v81, v82, v83
	v_add_f32_dpp v93, v93, v93 quad_perm:[2,3,0,1] row_mask:0xf bank_mask:0xf
	v_add_f32_dpp v92, v92, v92 row_ror:4 row_mask:0xf bank_mask:0xf
	v_cvt_pk_bf16_f32 v82, v84, v85
	v_add_f32_dpp v93, v93, v93 row_ror:4 row_mask:0xf bank_mask:0xf
	v_add_f32_dpp v92, v92, v92 row_ror:8 row_mask:0xf bank_mask:0xf
	v_cvt_pk_bf16_f32 v83, v86, v87
	v_add_f32_dpp v93, v93, v93 row_ror:8 row_mask:0xf bank_mask:0xf
	global_store_dwordx4 v6, v[80:83], s[54:55]
	s_and_saveexec_b64 s[58:59], s[8:9]
	s_cbranch_execz .Lrg_na0
	global_atomic_add_f32 v9, v92, s[18:19]
	global_atomic_add_f32 v9, v93, s[18:19] offset:4
.Lrg_na0:
	s_or_b64 exec, exec, s[58:59]
	v_add_u32_e32 v6, 0xfffe0000, v6
	v_add_u32_e32 v9, 0xfffffc00, v9
	s_waitcnt lgkmcnt(2)
	v_lshlrev_b32_e32 v80, 16, v236
	v_and_b32_e32 v81, 0xffff0000, v236
	v_lshlrev_b32_e32 v82, 16, v237
	v_and_b32_e32 v83, 0xffff0000, v237
	v_lshlrev_b32_e32 v84, 16, v238
	v_and_b32_e32 v85, 0xffff0000, v238
	v_lshlrev_b32_e32 v86, 16, v239
	v_and_b32_e32 v87, 0xffff0000, v239
	s_waitcnt vmcnt(3)
	v_lshlrev_b32_e32 v88, 16, v128
	v_and_b32_e32 v89, 0xffff0000, v128
	v_lshlrev_b32_e32 v90, 16, v129
	v_and_b32_e32 v91, 0xffff0000, v129
	v_lshlrev_b32_e32 v92, 16, v130
	v_and_b32_e32 v93, 0xffff0000, v130
	v_lshlrev_b32_e32 v94, 16, v131
	v_and_b32_e32 v95, 0xffff0000, v131
	v_add_f32_e32 v80, v88, v80
	v_add_f32_e32 v81, v89, v81
	v_add_f32_e32 v82, v90, v82
	v_add_f32_e32 v83, v91, v83
	v_add_f32_e32 v84, v92, v84
	v_add_f32_e32 v85, v93, v85
	v_add_f32_e32 v86, v94, v86
	v_add_f32_e32 v87, v95, v87
	v_add_f32_e32 v88, v80, v81
	v_add_f32_e32 v89, v82, v83
	v_add_f32_e32 v90, v84, v85
	v_add_f32_e32 v91, v86, v87
	v_mul_f32_e32 v12, v80, v80
	v_mul_f32_e32 v13, v82, v82
	v_mul_f32_e32 v14, v84, v84
	v_mul_f32_e32 v15, v86, v86
	v_add_f32_e32 v88, v88, v89
	v_add_f32_e32 v90, v90, v91
	v_fmac_f32_e32 v12, v81, v81
	v_fmac_f32_e32 v13, v83, v83
	v_fmac_f32_e32 v14, v85, v85
	v_fmac_f32_e32 v15, v87, v87
	v_add_f32_e32 v92, v88, v90
	v_add_f32_e32 v12, v12, v13
	v_add_f32_e32 v14, v14, v15
	v_add_f32_e32 v93, v12, v14
	v_add_f32_dpp v92, v92, v92 quad_perm:[1,0,3,2] row_mask:0xf bank_mask:0xf
	v_cvt_pk_bf16_f32 v80, v80, v81
	v_add_f32_dpp v93, v93, v93 quad_perm:[1,0,3,2] row_mask:0xf bank_mask:0xf
	v_add_f32_dpp v92, v92, v92 quad_perm:[2,3,0,1] row_mask:0xf bank_mask:0xf
	v_cvt_pk_bf16_f32 v81, v82, v83
	v_add_f32_dpp v93, v93, v93 quad_perm:[2,3,0,1] row_mask:0xf bank_mask:0xf
	v_add_f32_dpp v92, v92, v92 row_ror:4 row_mask:0xf bank_mask:0xf
	v_cvt_pk_bf16_f32 v82, v84, v85
	v_add_f32_dpp v93, v93, v93 row_ror:4 row_mask:0xf bank_mask:0xf
	v_add_f32_dpp v92, v92, v92 row_ror:8 row_mask:0xf bank_mask:0xf
	v_cvt_pk_bf16_f32 v83, v86, v87
	v_add_f32_dpp v93, v93, v93 row_ror:8 row_mask:0xf bank_mask:0xf
	global_store_dwordx4 v6, v[80:83], s[54:55]
	s_and_saveexec_b64 s[58:59], s[8:9]
	s_cbranch_execz .Lrg_na1
	global_atomic_add_f32 v9, v92, s[18:19]
	global_atomic_add_f32 v9, v93, s[18:19] offset:4
.Lrg_na1:
	s_or_b64 exec, exec, s[58:59]
	v_add_u32_e32 v6, 0xfffe0000, v6
	v_add_u32_e32 v9, 0xfffffc00, v9
	s_waitcnt lgkmcnt(1)
	v_lshlrev_b32_e32 v80, 16, v240
	v_and_b32_e32 v81, 0xffff0000, v240
	v_lshlrev_b32_e32 v82, 16, v241
	v_and_b32_e32 v83, 0xffff0000, v241
	v_lshlrev_b32_e32 v84, 16, v242
	v_and_b32_e32 v85, 0xffff0000, v242
	v_lshlrev_b32_e32 v86, 16, v243
	v_and_b32_e32 v87, 0xffff0000, v243
	s_waitcnt vmcnt(3)
	v_lshlrev_b32_e32 v88, 16, v132
	v_and_b32_e32 v89, 0xffff0000, v132
	v_lshlrev_b32_e32 v90, 16, v133
	v_and_b32_e32 v91, 0xffff0000, v133
	v_lshlrev_b32_e32 v92, 16, v134
	v_and_b32_e32 v93, 0xffff0000, v134
	v_lshlrev_b32_e32 v94, 16, v135
	v_and_b32_e32 v95, 0xffff0000, v135
	v_add_f32_e32 v80, v88, v80
	v_add_f32_e32 v81, v89, v81
	v_add_f32_e32 v82, v90, v82
	v_add_f32_e32 v83, v91, v83
	v_add_f32_e32 v84, v92, v84
	v_add_f32_e32 v85, v93, v85
	v_add_f32_e32 v86, v94, v86
	v_add_f32_e32 v87, v95, v87
	v_add_f32_e32 v88, v80, v81
	v_add_f32_e32 v89, v82, v83
	v_add_f32_e32 v90, v84, v85
	v_add_f32_e32 v91, v86, v87
	v_mul_f32_e32 v12, v80, v80
	v_mul_f32_e32 v13, v82, v82
	v_mul_f32_e32 v14, v84, v84
	v_mul_f32_e32 v15, v86, v86
	v_add_f32_e32 v88, v88, v89
	v_add_f32_e32 v90, v90, v91
	v_fmac_f32_e32 v12, v81, v81
	v_fmac_f32_e32 v13, v83, v83
	v_fmac_f32_e32 v14, v85, v85
	v_fmac_f32_e32 v15, v87, v87
	v_add_f32_e32 v92, v88, v90
	v_add_f32_e32 v12, v12, v13
	v_add_f32_e32 v14, v14, v15
	v_add_f32_e32 v93, v12, v14
	v_add_f32_dpp v92, v92, v92 quad_perm:[1,0,3,2] row_mask:0xf bank_mask:0xf
	v_cvt_pk_bf16_f32 v80, v80, v81
	v_add_f32_dpp v93, v93, v93 quad_perm:[1,0,3,2] row_mask:0xf bank_mask:0xf
	v_add_f32_dpp v92, v92, v92 quad_perm:[2,3,0,1] row_mask:0xf bank_mask:0xf
	v_cvt_pk_bf16_f32 v81, v82, v83
	v_add_f32_dpp v93, v93, v93 quad_perm:[2,3,0,1] row_mask:0xf bank_mask:0xf
	v_add_f32_dpp v92, v92, v92 row_ror:4 row_mask:0xf bank_mask:0xf
	v_cvt_pk_bf16_f32 v82, v84, v85
	v_add_f32_dpp v93, v93, v93 row_ror:4 row_mask:0xf bank_mask:0xf
	v_add_f32_dpp v92, v92, v92 row_ror:8 row_mask:0xf bank_mask:0xf
	v_cvt_pk_bf16_f32 v83, v86, v87
	v_add_f32_dpp v93, v93, v93 row_ror:8 row_mask:0xf bank_mask:0xf
	global_store_dwordx4 v6, v[80:83], s[54:55]
	s_and_saveexec_b64 s[58:59], s[8:9]
	s_cbranch_execz .Lrg_na2
	global_atomic_add_f32 v9, v92, s[18:19]
	global_atomic_add_f32 v9, v93, s[18:19] offset:4
.Lrg_na2:
	s_or_b64 exec, exec, s[58:59]
	v_add_u32_e32 v6, 0xfffe0000, v6
	v_add_u32_e32 v9, 0xfffffc00, v9
	s_waitcnt lgkmcnt(0)
	v_lshlrev_b32_e32 v80, 16, v244
	v_and_b32_e32 v81, 0xffff0000, v244
	v_lshlrev_b32_e32 v82, 16, v245
	v_and_b32_e32 v83, 0xffff0000, v245
	v_lshlrev_b32_e32 v84, 16, v246
	v_and_b32_e32 v85, 0xffff0000, v246
	v_lshlrev_b32_e32 v86, 16, v247
	v_and_b32_e32 v87, 0xffff0000, v247
	s_waitcnt vmcnt(3)
	v_lshlrev_b32_e32 v88, 16, v136
	v_and_b32_e32 v89, 0xffff0000, v136
	v_lshlrev_b32_e32 v90, 16, v137
	v_and_b32_e32 v91, 0xffff0000, v137
	v_lshlrev_b32_e32 v92, 16, v138
	v_and_b32_e32 v93, 0xffff0000, v138
	v_lshlrev_b32_e32 v94, 16, v139
	v_and_b32_e32 v95, 0xffff0000, v139
	v_add_f32_e32 v80, v88, v80
	v_add_f32_e32 v81, v89, v81
	v_add_f32_e32 v82, v90, v82
	v_add_f32_e32 v83, v91, v83
	v_add_f32_e32 v84, v92, v84
	v_add_f32_e32 v85, v93, v85
	v_add_f32_e32 v86, v94, v86
	v_add_f32_e32 v87, v95, v87
	v_add_f32_e32 v88, v80, v81
	v_add_f32_e32 v89, v82, v83
	v_add_f32_e32 v90, v84, v85
	v_add_f32_e32 v91, v86, v87
	v_mul_f32_e32 v12, v80, v80
	v_mul_f32_e32 v13, v82, v82
	v_mul_f32_e32 v14, v84, v84
	v_mul_f32_e32 v15, v86, v86
	v_add_f32_e32 v88, v88, v89
	v_add_f32_e32 v90, v90, v91
	v_fmac_f32_e32 v12, v81, v81
	v_fmac_f32_e32 v13, v83, v83
	v_fmac_f32_e32 v14, v85, v85
	v_fmac_f32_e32 v15, v87, v87
	v_add_f32_e32 v92, v88, v90
	v_add_f32_e32 v12, v12, v13
	v_add_f32_e32 v14, v14, v15
	v_add_f32_e32 v93, v12, v14
	v_add_f32_dpp v92, v92, v92 quad_perm:[1,0,3,2] row_mask:0xf bank_mask:0xf
	v_cvt_pk_bf16_f32 v80, v80, v81
	v_add_f32_dpp v93, v93, v93 quad_perm:[1,0,3,2] row_mask:0xf bank_mask:0xf
	v_add_f32_dpp v92, v92, v92 quad_perm:[2,3,0,1] row_mask:0xf bank_mask:0xf
	v_cvt_pk_bf16_f32 v81, v82, v83
	v_add_f32_dpp v93, v93, v93 quad_perm:[2,3,0,1] row_mask:0xf bank_mask:0xf
	v_add_f32_dpp v92, v92, v92 row_ror:4 row_mask:0xf bank_mask:0xf
	v_cvt_pk_bf16_f32 v82, v84, v85
	v_add_f32_dpp v93, v93, v93 row_ror:4 row_mask:0xf bank_mask:0xf
	v_add_f32_dpp v92, v92, v92 row_ror:8 row_mask:0xf bank_mask:0xf
	v_cvt_pk_bf16_f32 v83, v86, v87
	v_add_f32_dpp v93, v93, v93 row_ror:8 row_mask:0xf bank_mask:0xf
	global_store_dwordx4 v6, v[80:83], s[54:55]
	s_and_saveexec_b64 s[58:59], s[8:9]
	s_cbranch_execz .Lrg_na3
	global_atomic_add_f32 v9, v92, s[18:19]
	global_atomic_add_f32 v9, v93, s[18:19] offset:4
